# indexer running-compaction bisection: the 8 compares per bit go to separate SGPR pairs instead of serialising through vcc
# speedup vs baseline: 1.0421x; 1.0029x over previous
; template <bool EXACT>
; __device__ void select256(LAS unsigned char* lds, int qi, int wid, int lane) {
;     ...
;     int cT = m;
; #pragma unroll 1
;     ...
;         const unsigned trial = T | (1u << bit);
;         int c = 0;
; #pragma unroll
;         for (int i = 0; i < 8; ++i) c += __builtin_popcountll(__ballot(k[i] >= trial));
;         if (c >= 256) { T = trial; cT = c; }
;         if (!EXACT && cT <= 320) break;
;     }
;     if (!EXACT) {
;         int base = 0;
; #pragma unroll
;         for (int i = 0; i < 8; ++i) {
;             const bool keep = k[i] >= T;
;             const u64 bm = __ballot(keep);
;             const int pos = base + __builtin_popcountll(bm & ((1ull << lane) - 1ull));
;             if (keep) cand[pos] = e[i];
;             base += __builtin_popcountll(bm);
;         }
;         if (lane == 0) { cnt[qi] = (unsigned)base; cnt[32 + qi] = T - 1u; }
.LBB0_665:
	v_lshlrev_b32_e64 v114, v113, 1
	v_or_b32_e32 v114, v114, v33
	v_cmp_le_u32_e32 vcc, v114, v112
	v_cmp_le_u32_e64 s[26:27], v114, v111
	v_cmp_le_u32_e64 s[34:35], v114, v110
	v_cmp_le_u32_e64 s[36:37], v114, v109
	v_cmp_le_u32_e64 s[38:39], v114, v108
	v_cmp_le_u32_e64 s[40:41], v114, v45
	v_cmp_le_u32_e64 s[44:45], v114, v39
	v_cmp_le_u32_e64 s[70:71], v114, v37
	s_bcnt1_i32_b64 s28, vcc
	s_bcnt1_i32_b64 s29, s[26:27]
	s_add_i32 s28, s28, s29
	s_bcnt1_i32_b64 s29, s[34:35]
	s_add_i32 s28, s28, s29
	s_bcnt1_i32_b64 s29, s[36:37]
	s_add_i32 s28, s28, s29
	s_bcnt1_i32_b64 s29, s[38:39]
	s_add_i32 s28, s28, s29
	s_bcnt1_i32_b64 s29, s[40:41]
	s_add_i32 s28, s28, s29
	s_bcnt1_i32_b64 s29, s[44:45]
	s_add_i32 s28, s28, s29
	s_bcnt1_i32_b64 s29, s[70:71]
	s_add_i32 s28, s28, s29
	s_cmpk_gt_u32 s28, 0xff
	s_cselect_b32 s31, s28, s31
	s_cselect_b64 vcc, -1, 0
	s_cmpk_lt_i32 s31, 0x141
	v_cndmask_b32_e32 v33, v33, v114, vcc
	s_cselect_b64 s[28:29], -1, 0
	v_subrev_co_u32_e32 v113, vcc, 1, v113
	s_or_b64 s[28:29], s[28:29], vcc
	s_andn2_b64 vcc, exec, s[28:29]
	s_cbranch_vccnz .LBB0_665
	v_cmp_le_u32_e32 vcc, v33, v112
	s_and_saveexec_b64 s[28:29], vcc
	s_cbranch_execz .LBB0_668
	v_and_b32_e32 v113, vcc_lo, v58
	v_and_b32_e32 v112, vcc_hi, v57
	v_bcnt_u32_b32 v113, v113, 0
	v_bcnt_u32_b32 v112, v112, v113
	v_lshl_add_u32 v112, v112, 3, s93
	ds_write_b64 v112, v[68:69] offset:35072
